# scan3 epilogue: ds_swizzle butterflies replaced by DPP moves (bitwise-identical all-reduce)
# speedup vs baseline: 1.0047x; 1.0039x over previous
; __device__ __forceinline__ float bf2f(unsigned h) { return __uint_as_float(h << 16); }
; __device__ __forceinline__ unsigned pk2(float lo, float hi) { return pg8::cvt_pk_bf16(lo, hi); }
; template <int X> __device__ __forceinline__ float xor_lane(float v) { static_assert(X >= 1 && X <= 16, "xor_lane"); return __int_as_float(__builtin_amdgcn_ds_swizzle(__float_as_int(v), (X << 10) | 0x1F)); }
; __global__ void __launch_bounds__(512, 2) fwd_megakernel(Args args) {
;     ...
;                     for (int r = 0; r < 4; ++r) { const int i = 16 * w4 + 4 * kk + r;
;                         float x0 = O[0][r], x1 = O[1][r], x2 = O[2][r], x3 = O[3][r];
;                         if (grp == 0) { float sm = (x0 + x1) + (x2 + x3); sm += xor_lane<1>(sm); sm += xor_lane<2>(sm); sm += xor_lane<4>(sm); sm += xor_lane<8>(sm);
;                             const float mean = sm * (1.f / 64.f); x0 -= mean; x1 -= mean; x2 -= mean; x3 -= mean; }
;                         float sq = (x0 * x0 + x1 * x1) + (x2 * x2 + x3 * x3); sq += xor_lane<1>(sq); sq += xor_lane<2>(sq); sq += xor_lane<4>(sq); sq += xor_lane<8>(sq);
;                         const float rs = rsqrtf(sq * (1.f / 64.f) + NEPS);
;                         const float xs[4] = {x0 * rs, x1 * rs, x2 * rs, x3 * rs};
;                         u16* yp = XNY + (size_t)(row0 + i) * 1024 + grp * 256 + h * 64 + nn;
; #pragma unroll
;                         for (int et = 0; et < 4; ++et) { const float gate = bf2f(graw[r][et]); const float sg = gate * __builtin_amdgcn_rcpf(1.f + __expf(-gate)); yp[16 * et] = (u16)(pk2(sg * xs[et], 0.f) & 0xffffu); } }
;                     __syncthreads();
.LBB0_146:
	v_mov_b32_e32 v6, v5
	v_mov_b32_e32 v7, v9
	v_mov_b32_e32 v2, v4
	v_mov_b32_e32 v3, v8
	v_pk_mul_f32 v[6:7], v[6:7], v[6:7]
	v_readlane_b32 s10, v239, 60
	v_pk_fma_f32 v[2:3], v[2:3], v[2:3], v[6:7]
	v_lshlrev_b32_e32 v6, 16, v104
	v_add_f32_e32 v0, v2, v3
	s_nop 1
	v_mov_b32_dpp v2, v0 quad_perm:[1,0,3,2] row_mask:0xf bank_mask:0xf
	v_mul_f32_e32 v10, 0xbfb8aa3b, v6
	v_exp_f32_e32 v10, v10
	v_lshlrev_b32_e32 v7, 16, v103
	s_add_i32 s29, s29, s94
	s_waitcnt lgkmcnt(0)
	v_add_f32_e32 v2, v0, v2
	s_nop 1
	v_mov_b32_dpp v3, v2 quad_perm:[2,3,0,1] row_mask:0xf bank_mask:0xf
	v_add_f32_e32 v10, 1.0, v10
	v_or_b32_e32 v0, 3, v20
	v_rcp_f32_e32 v10, v10
	s_add_i32 s28, s28, s10
	s_waitcnt lgkmcnt(0)
	v_add_f32_e32 v2, v2, v3
	s_nop 1
	v_mov_b32_dpp v3, v2 row_half_mirror row_mask:0xf bank_mask:0xf
	v_mul_f32_e32 v6, v10, v6
	s_cmpk_gt_i32 s29, 0x81f
	s_waitcnt lgkmcnt(0)
	v_add_f32_e32 v11, v2, v3
	s_nop 1
	v_mov_b32_dpp v12, v11 row_mirror row_mask:0xf bank_mask:0xf
	v_lshlrev_b64 v[2:3], 11, v[0:1]
	v_mul_f32_e32 v0, 0xbfb8aa3b, v7
	v_exp_f32_e32 v0, v0
	v_lshl_add_u64 v[2:3], v[18:19], 0, v[2:3]
	s_waitcnt lgkmcnt(0)
	v_add_f32_e32 v11, v11, v12
	v_fmamk_f32 v11, v11, 0x3c800000, v215
	v_mul_f32_e32 v12, 0x4b800000, v11
	v_cmp_gt_f32_e32 vcc, s77, v11
	v_add_f32_e32 v0, 1.0, v0
	v_rcp_f32_e32 v0, v0
	v_cndmask_b32_e32 v11, v11, v12, vcc
	v_rsq_f32_e32 v11, v11
	v_mul_f32_e32 v0, v0, v7
	v_mul_f32_e32 v10, 0x45800000, v11
	v_cndmask_b32_e32 v10, v11, v10, vcc
	v_mul_f32_e32 v4, v4, v10
	v_mul_f32_e32 v4, v4, v6
	v_lshlrev_b32_e32 v6, 16, v102
	v_mul_f32_e32 v5, v5, v10
	v_mul_f32_e32 v8, v8, v10
	v_mul_f32_e32 v9, v9, v10
	v_mul_f32_e32 v10, 0xbfb8aa3b, v6
	v_exp_f32_e32 v10, v10
	v_cvt_pk_bf16_f32 v4, v4, v1
	v_mul_f32_e32 v0, v5, v0
	v_lshlrev_b32_e32 v5, 16, v101
	global_store_short v[2:3], v4, off
	v_add_f32_e32 v4, 1.0, v10
	v_mul_f32_e32 v7, 0xbfb8aa3b, v5
	v_rcp_f32_e32 v4, v4
	v_exp_f32_e32 v7, v7
	v_cvt_pk_bf16_f32 v0, v0, v1
	global_store_short v[2:3], v0, off offset:32
	v_mul_f32_e32 v0, v4, v6
	v_add_f32_e32 v4, 1.0, v7
	v_rcp_f32_e32 v4, v4
	v_mul_f32_e32 v0, v8, v0
	v_cvt_pk_bf16_f32 v0, v0, v1
	global_store_short v[2:3], v0, off offset:64
	v_mul_f32_e32 v0, v4, v5
	v_mul_f32_e32 v0, v9, v0
	v_cvt_pk_bf16_f32 v0, v0, v1
	global_store_short v[2:3], v0, off offset:96
	s_barrier
	s_cbranch_scc1 .LBB0_183

; #define LAS __attribute__((address_space(3)))
; __global__ void __launch_bounds__(512, 2) fwd_megakernel(Args args) {
;     ...
;                         u32x4 pa; pa.x = pk2(sc[2 * p2][0], sc[2 * p2][1]); pa.y = pk2(sc[2 * p2][2], sc[2 * p2][3]); pa.z = pk2(sc[2 * p2 + 1][0], sc[2 * p2 + 1][1]); pa.w = pk2(sc[2 * p2 + 1][2], sc[2 * p2 + 1][3]);
;                         const mbf16x8 af = __builtin_bit_cast(mbf16x8, pa);
; #pragma unroll
;                         for (int et = 0; et < 4; ++et) {
;                             typedef short trv4_t __attribute__((ext_vector_type(4)));
;                             const LAS u16* vp = VT + (32 * p2 + 4 * kk + (nn >> 2)) * 68 + 16 * et + 4 * (nn & 3);
;                             const trv4_t lo = __builtin_amdgcn_ds_read_tr16_b64_v4i16((LAS trv4_t*)vp), hi = __builtin_amdgcn_ds_read_tr16_b64_v4i16((LAS trv4_t*)(vp + 16 * 68));
;                             O[et] = __builtin_amdgcn_mfma_f32_16x16x32_bf16(af, (mbf16x8){lo[0], lo[1], lo[2], lo[3], hi[0], hi[1], hi[2], hi[3]}, O[et], 0, 0, 0); }
;                     }
; #pragma unroll
;                     for (int et = 0; et < 4; ++et) { const LAS u16* sp = ST + (16 * et + nn) * 72 + 8 * kk;
;                         O[et] = __builtin_amdgcn_mfma_f32_16x16x32_bf16(qfr_f, *(const LAS mbf16x8*)sp, O[et], 0, 0, 0);
;                         O[et] = __builtin_amdgcn_mfma_f32_16x16x32_bf16(qfr_b, *(const LAS mbf16x8*)(sp + 32), O[et], 0, 0, 0); }
; #pragma unroll
;                     for (int r = 0; r < 4; ++r) { const int i = 16 * w4 + 4 * kk + r;
;                         float x0 = O[0][r], x1 = O[1][r], x2 = O[2][r], x3 = O[3][r];
;                         if (grp == 0) { float sm = (x0 + x1) + (x2 + x3); sm += xor_lane<1>(sm); sm += xor_lane<2>(sm); sm += xor_lane<4>(sm); sm += xor_lane<8>(sm);
;                             const float mean = sm * (1.f / 64.f); x0 -= mean; x1 -= mean; x2 -= mean; x3 -= mean; }
;                         float sq = (x0 * x0 + x1 * x1) + (x2 * x2 + x3 * x3); sq += xor_lane<1>(sq); sq += xor_lane<2>(sq); sq += xor_lane<4>(sq); sq += xor_lane<8>(sq);
;                         const float rs = rsqrtf(sq * (1.f / 64.f) + NEPS);
;                         const float xs[4] = {x0 * rs, x1 * rs, x2 * rs, x3 * rs};
;                         u16* yp = XNY + (size_t)(row0 + i) * 1024 + grp * 256 + h * 64 + nn;
; #pragma unroll
.LBB0_173:
	v_cvt_pk_bf16_f32 v2, v2, v3
	v_cvt_pk_bf16_f32 v3, v4, v5
	v_cvt_pk_bf16_f32 v4, v6, v7
	v_cvt_pk_bf16_f32 v5, v8, v9
	ds_read_b64_tr_b16 v[8:9], v99 offset:12416
	ds_read_b64_tr_b16 v[6:7], v99 offset:10240
	s_waitcnt lgkmcnt(2)
	ds_read_b64_tr_b16 v[18:19], v99 offset:10272
	ds_read_b64_tr_b16 v[20:21], v99 offset:12448
	ds_read_b64_tr_b16 v[22:23], v99 offset:10304
	ds_read_b64_tr_b16 v[24:25], v99 offset:12480
	ds_read_b64_tr_b16 v[26:27], v99 offset:10336
	ds_read_b64_tr_b16 v[28:29], v99 offset:12512
	s_waitcnt lgkmcnt(6)
	v_mfma_f32_16x16x32_bf16 v[6:9], v[2:5], v[6:9], 0
	v_cvt_pk_bf16_f32 v10, v10, v11
	v_cvt_pk_bf16_f32 v11, v12, v13
	v_cvt_pk_bf16_f32 v12, v14, v15
	s_waitcnt lgkmcnt(4)
	v_mfma_f32_16x16x32_bf16 v[18:21], v[2:5], v[18:21], 0
	v_cvt_pk_bf16_f32 v13, v16, v17
	v_cndmask_b32_e64 v0, 0, 1, s[60:61]
	v_cmp_ne_u32_e64 s[46:47], 1, v0
	s_waitcnt lgkmcnt(2)
	v_mfma_f32_16x16x32_bf16 v[22:25], v[2:5], v[22:25], 0
	s_andn2_b64 vcc, exec, s[60:61]
	s_waitcnt lgkmcnt(0)
	v_mfma_f32_16x16x32_bf16 v[2:5], v[2:5], v[26:29], 0
	ds_read_b64_tr_b16 v[16:17], v99 offset:16768
	ds_read_b64_tr_b16 v[14:15], v99 offset:14592
	ds_read_b64_tr_b16 v[26:27], v99 offset:14624
	ds_read_b64_tr_b16 v[28:29], v99 offset:16800
	s_waitcnt lgkmcnt(2)
	v_mfma_f32_16x16x32_bf16 v[6:9], v[10:13], v[14:17], v[6:9]
	s_waitcnt lgkmcnt(0)
	v_mfma_f32_16x16x32_bf16 v[14:17], v[10:13], v[26:29], v[18:21]
	s_nop 2
	ds_read_b64_tr_b16 v[18:19], v99 offset:14656
	ds_read_b64_tr_b16 v[20:21], v99 offset:16832
	s_waitcnt lgkmcnt(0)
	v_mfma_f32_16x16x32_bf16 v[18:21], v[10:13], v[18:21], v[22:25]
	s_nop 2
	ds_read_b64_tr_b16 v[22:23], v99 offset:14688
	ds_read_b64_tr_b16 v[24:25], v99 offset:16864
	s_waitcnt lgkmcnt(0)
	v_mfma_f32_16x16x32_bf16 v[22:25], v[10:13], v[22:25], v[2:5]
	s_nop 2
	ds_read_b128 v[2:5], v100 offset:19456
	s_waitcnt lgkmcnt(0)
	v_mfma_f32_16x16x32_bf16 v[2:5], v[30:33], v[2:5], v[6:9]
	s_nop 2
	ds_read_b128 v[6:9], v100 offset:19520
	s_waitcnt lgkmcnt(0)
	v_mfma_f32_16x16x32_bf16 v[10:13], v[34:37], v[6:9], v[2:5]
	ds_read_b128 v[6:9], v100 offset:21824
	s_nop 1
	ds_read_b128 v[2:5], v100 offset:21760
	s_waitcnt lgkmcnt(0)
	v_mfma_f32_16x16x32_bf16 v[2:5], v[30:33], v[2:5], v[14:17]
	s_nop 2
	ds_read_b128 v[14:17], v100 offset:24128
	v_mfma_f32_16x16x32_bf16 v[2:5], v[34:37], v[6:9], v[2:5]
	ds_read_b128 v[6:9], v100 offset:24064
	s_waitcnt lgkmcnt(0)
	v_mfma_f32_16x16x32_bf16 v[6:9], v[30:33], v[6:9], v[18:21]
	s_nop 2
	ds_read_b128 v[18:21], v100 offset:26432
	v_mfma_f32_16x16x32_bf16 v[14:17], v[34:37], v[14:17], v[6:9]
	s_nop 2
	ds_read_b128 v[6:9], v100 offset:26368
	s_waitcnt lgkmcnt(0)
	v_mfma_f32_16x16x32_bf16 v[6:9], v[30:33], v[6:9], v[22:25]
	v_mfma_f32_16x16x32_bf16 v[6:9], v[34:37], v[18:21], v[6:9]
	s_cbranch_vccnz .LBB0_175
	v_mov_b32_e32 v18, v10
	v_mov_b32_e32 v19, v14
	v_mov_b32_e32 v20, v2
	s_nop 3
	v_mov_b32_e32 v21, v6
	v_pk_add_f32 v[18:19], v[18:19], v[20:21]
	v_mov_b32_e32 v20, v14
	v_add_f32_e32 v0, v18, v19
	s_nop 1
	v_mov_b32_dpp v18, v0 quad_perm:[1,0,3,2] row_mask:0xf bank_mask:0xf
	v_mov_b32_e32 v19, v2
	s_waitcnt lgkmcnt(0)
	v_add_f32_e32 v0, v0, v18
	s_nop 1
	v_mov_b32_dpp v18, v0 quad_perm:[2,3,0,1] row_mask:0xf bank_mask:0xf
	s_waitcnt lgkmcnt(0)
	v_add_f32_e32 v0, v0, v18
	s_nop 1
	v_mov_b32_dpp v18, v0 row_half_mirror row_mask:0xf bank_mask:0xf
	s_waitcnt lgkmcnt(0)
	v_add_f32_e32 v0, v0, v18
	s_nop 1
	v_mov_b32_dpp v22, v0 row_mirror row_mask:0xf bank_mask:0xf
	v_mov_b32_e32 v18, v10
	s_waitcnt lgkmcnt(0)
	v_add_f32_e32 v0, v0, v22
	v_mul_f32_e32 v0, 0x3c800000, v0
	v_pk_add_f32 v[18:19], v[18:19], v[0:1] op_sel_hi:[1,0] neg_lo:[0,1] neg_hi:[0,1]
	v_pk_add_f32 v[20:21], v[20:21], v[0:1] op_sel_hi:[1,0] neg_lo:[0,1] neg_hi:[0,1]
	v_mov_b32_e32 v10, v18
	v_mov_b32_e32 v2, v19
	v_mov_b32_e32 v14, v20
	v_mov_b32_e32 v6, v21
.LBB0_175:
	s_lshl_b32 s14, s30, 8
	s_ashr_i32 s15, s14, 31
	s_lshl_b64 s[14:15], s[14:15], 1
	s_add_u32 s10, s36, s14
	s_addc_u32 s15, s37, s15
	s_lshl_b32 s14, s55, 1
	v_mov_b32_e32 v24, v2
	v_mov_b32_e32 v25, v6
	s_add_u32 s14, s10, s14
	v_mov_b32_e32 v22, v10
	v_mov_b32_e32 v23, v14
	v_pk_mul_f32 v[24:25], v[24:25], v[24:25]
	s_addc_u32 s15, s15, 0
	v_lshlrev_b32_e32 v0, 1, v66
	v_pk_fma_f32 v[22:23], v[22:23], v[22:23], v[24:25]
	v_lshl_add_u64 v[18:19], s[14:15], 0, v[0:1]
	v_add_f32_e32 v0, v22, v23
	s_nop 1
	v_mov_b32_dpp v21, v0 quad_perm:[1,0,3,2] row_mask:0xf bank_mask:0xf
	v_or_b32_e32 v20, s31, v71
	s_waitcnt lgkmcnt(0)
	v_add_f32_e32 v0, v0, v21
	s_nop 1
	v_mov_b32_dpp v21, v0 quad_perm:[2,3,0,1] row_mask:0xf bank_mask:0xf
	s_waitcnt lgkmcnt(0)
	v_add_f32_e32 v0, v0, v21
	s_nop 1
	v_mov_b32_dpp v21, v0 row_half_mirror row_mask:0xf bank_mask:0xf
	s_waitcnt lgkmcnt(0)
	v_add_f32_e32 v0, v0, v21
	s_nop 1
	v_mov_b32_dpp v21, v0 row_mirror row_mask:0xf bank_mask:0xf
	s_waitcnt lgkmcnt(0)
	v_add_f32_e32 v0, v0, v21
	v_fmamk_f32 v0, v0, 0x3c800000, v215
	v_cmp_gt_f32_e32 vcc, s77, v0
	v_mul_f32_e32 v21, 0x4b800000, v0
	s_nop 0
	v_cndmask_b32_e32 v0, v0, v21, vcc
	v_rsq_f32_e32 v0, v0
	s_nop 0
	v_mul_f32_e32 v21, 0x45800000, v0
	v_cndmask_b32_e32 v0, v0, v21, vcc
	v_mul_f32_e32 v10, v10, v0
	v_mul_f32_e32 v2, v2, v0
	v_mul_f32_e32 v14, v14, v0
	v_mul_f32_e32 v0, v6, v0
	v_mov_b32_e32 v21, v1
	v_lshlrev_b32_e32 v6, 16, v116
	v_lshlrev_b64 v[22:23], 11, v[20:21]
	v_mul_f32_e32 v21, 0xbfb8aa3b, v6
	v_exp_f32_e32 v21, v21
	v_lshl_add_u64 v[22:23], v[18:19], 0, v[22:23]
	s_and_b64 vcc, exec, s[46:47]
	v_add_f32_e32 v21, 1.0, v21
	v_rcp_f32_e32 v21, v21
	s_nop 0
	v_mul_f32_e32 v6, v21, v6
	v_mul_f32_e32 v6, v10, v6
	v_cvt_pk_bf16_f32 v6, v6, v1
	global_store_short v[22:23], v6, off
	v_lshlrev_b32_e32 v6, 16, v115
	v_mul_f32_e32 v10, 0xbfb8aa3b, v6
	v_exp_f32_e32 v10, v10
	s_nop 0
	v_add_f32_e32 v10, 1.0, v10
	v_rcp_f32_e32 v10, v10
	s_nop 0
	v_mul_f32_e32 v6, v10, v6
	v_mul_f32_e32 v2, v2, v6
	v_cvt_pk_bf16_f32 v2, v2, v1
	global_store_short v[22:23], v2, off offset:32
	v_lshlrev_b32_e32 v2, 16, v114
	v_mul_f32_e32 v6, 0xbfb8aa3b, v2
	v_exp_f32_e32 v6, v6
	s_nop 0
	v_add_f32_e32 v6, 1.0, v6
	v_rcp_f32_e32 v6, v6
	s_nop 0
	v_mul_f32_e32 v2, v6, v2
	v_mul_f32_e32 v2, v14, v2
	v_cvt_pk_bf16_f32 v2, v2, v1
	global_store_short v[22:23], v2, off offset:64
	v_lshlrev_b32_e32 v2, 16, v113
	v_mul_f32_e32 v6, 0xbfb8aa3b, v2
	v_exp_f32_e32 v6, v6
	s_nop 0
	v_add_f32_e32 v6, 1.0, v6
	v_rcp_f32_e32 v6, v6
	s_nop 0
	v_mul_f32_e32 v2, v6, v2
	v_mul_f32_e32 v0, v0, v2
	v_mov_b32_e32 v2, v11
	v_mov_b32_e32 v6, v15
	v_cvt_pk_bf16_f32 v0, v0, v1
	global_store_short v[22:23], v0, off offset:96
	s_cbranch_vccnz .LBB0_177
; __device__ __forceinline__ float bf2f(unsigned h) { return __uint_as_float(h << 16); }
; __device__ __forceinline__ unsigned pk2(float lo, float hi) { return pg8::cvt_pk_bf16(lo, hi); }
; template <int X> __device__ __forceinline__ float xor_lane(float v) { static_assert(X >= 1 && X <= 16, "xor_lane"); return __int_as_float(__builtin_amdgcn_ds_swizzle(__float_as_int(v), (X << 10) | 0x1F)); }
; __global__ void __launch_bounds__(512, 2) fwd_megakernel(Args args) {
;     ...
;                     for (int r = 0; r < 4; ++r) { const int i = 16 * w4 + 4 * kk + r;
;                         float x0 = O[0][r], x1 = O[1][r], x2 = O[2][r], x3 = O[3][r];
;                         if (grp == 0) { float sm = (x0 + x1) + (x2 + x3); sm += xor_lane<1>(sm); sm += xor_lane<2>(sm); sm += xor_lane<4>(sm); sm += xor_lane<8>(sm);
;                             const float mean = sm * (1.f / 64.f); x0 -= mean; x1 -= mean; x2 -= mean; x3 -= mean; }
;                         float sq = (x0 * x0 + x1 * x1) + (x2 * x2 + x3 * x3); sq += xor_lane<1>(sq); sq += xor_lane<2>(sq); sq += xor_lane<4>(sq); sq += xor_lane<8>(sq);
;                         const float rs = rsqrtf(sq * (1.f / 64.f) + NEPS);
;                         const float xs[4] = {x0 * rs, x1 * rs, x2 * rs, x3 * rs};
;                         u16* yp = XNY + (size_t)(row0 + i) * 1024 + grp * 256 + h * 64 + nn;
; #pragma unroll
;                         for (int et = 0; et < 4; ++et) { const float gate = bf2f(graw[r][et]); const float sg = gate * __builtin_amdgcn_rcpf(1.f + __expf(-gate)); yp[16 * et] = (u16)(pk2(sg * xs[et], 0.f) & 0xffffu); } }
	v_mov_b32_e32 v14, v11
	v_mov_b32_e32 v10, v3
	v_mov_b32_e32 v11, v7
	v_pk_add_f32 v[10:11], v[14:15], v[10:11]
	s_nop 0
	v_add_f32_e32 v0, v10, v11
	s_nop 1
	v_mov_b32_dpp v10, v0 quad_perm:[1,0,3,2] row_mask:0xf bank_mask:0xf
	s_waitcnt lgkmcnt(0)
	v_add_f32_e32 v0, v0, v10
	s_nop 1
	v_mov_b32_dpp v10, v0 quad_perm:[2,3,0,1] row_mask:0xf bank_mask:0xf
	s_waitcnt lgkmcnt(0)
	v_add_f32_e32 v0, v0, v10
	s_nop 1
	v_mov_b32_dpp v10, v0 row_half_mirror row_mask:0xf bank_mask:0xf
	s_waitcnt lgkmcnt(0)
	v_add_f32_e32 v0, v0, v10
	s_nop 1
	v_mov_b32_dpp v10, v0 row_mirror row_mask:0xf bank_mask:0xf
	s_waitcnt lgkmcnt(0)
	v_add_f32_e32 v0, v0, v10
	v_mul_f32_e32 v0, 0x3c800000, v0
	v_pk_add_f32 v[2:3], v[2:3], v[0:1] op_sel_hi:[1,0] neg_lo:[0,1] neg_hi:[0,1]
	v_pk_add_f32 v[6:7], v[6:7], v[0:1] op_sel_hi:[1,0] neg_lo:[0,1] neg_hi:[0,1]
.LBB0_177:
	v_mov_b32_e32 v14, v3
	v_mov_b32_e32 v15, v7
	v_mov_b32_e32 v10, v2
	v_mov_b32_e32 v11, v6
	v_pk_mul_f32 v[14:15], v[14:15], v[14:15]
	s_nop 0
	v_pk_fma_f32 v[10:11], v[10:11], v[10:11], v[14:15]
	s_nop 0
	v_add_f32_e32 v0, v10, v11
	s_nop 1
	v_mov_b32_dpp v10, v0 quad_perm:[1,0,3,2] row_mask:0xf bank_mask:0xf
	s_waitcnt lgkmcnt(0)
	v_add_f32_e32 v0, v0, v10
	s_nop 1
	v_mov_b32_dpp v10, v0 quad_perm:[2,3,0,1] row_mask:0xf bank_mask:0xf
	s_waitcnt lgkmcnt(0)
	v_add_f32_e32 v0, v0, v10
	s_nop 1
	v_mov_b32_dpp v10, v0 row_half_mirror row_mask:0xf bank_mask:0xf
	s_waitcnt lgkmcnt(0)
	v_add_f32_e32 v0, v0, v10
	s_nop 1
	v_mov_b32_dpp v10, v0 row_mirror row_mask:0xf bank_mask:0xf
	s_waitcnt lgkmcnt(0)
	v_add_f32_e32 v0, v0, v10
	v_fmamk_f32 v0, v0, 0x3c800000, v215
	v_cmp_gt_f32_e32 vcc, s77, v0
	v_mul_f32_e32 v10, 0x4b800000, v0
	s_nop 0
	v_cndmask_b32_e32 v0, v0, v10, vcc
	v_rsq_f32_e32 v0, v0
	s_nop 0
	v_mul_f32_e32 v10, 0x45800000, v0
	v_cndmask_b32_e32 v0, v0, v10, vcc
	v_mul_f32_e32 v10, v2, v0
	v_mul_f32_e32 v11, v3, v0
	v_mul_f32_e32 v6, v6, v0
	v_mul_f32_e32 v7, v7, v0
	v_or_b32_e32 v0, 1, v20
	v_lshlrev_b64 v[2:3], 11, v[0:1]
	v_lshlrev_b32_e32 v0, 16, v112
	v_mul_f32_e32 v14, 0xbfb8aa3b, v0
	v_exp_f32_e32 v14, v14
	v_lshl_add_u64 v[2:3], v[18:19], 0, v[2:3]
	s_and_b64 vcc, exec, s[46:47]
	v_add_f32_e32 v14, 1.0, v14
	v_rcp_f32_e32 v14, v14
	s_nop 0
	v_mul_f32_e32 v0, v14, v0
	v_mul_f32_e32 v0, v10, v0
	v_cvt_pk_bf16_f32 v0, v0, v1
	global_store_short v[2:3], v0, off
	v_lshlrev_b32_e32 v0, 16, v111
	v_mul_f32_e32 v10, 0xbfb8aa3b, v0
	v_exp_f32_e32 v10, v10
	s_nop 0
	v_add_f32_e32 v10, 1.0, v10
	v_rcp_f32_e32 v10, v10
	s_nop 0
	v_mul_f32_e32 v0, v10, v0
	v_mul_f32_e32 v0, v11, v0
	v_cvt_pk_bf16_f32 v0, v0, v1
	global_store_short v[2:3], v0, off offset:32
	v_lshlrev_b32_e32 v0, 16, v110
	v_mul_f32_e32 v10, 0xbfb8aa3b, v0
	v_exp_f32_e32 v10, v10
	s_nop 0
	v_add_f32_e32 v10, 1.0, v10
	v_rcp_f32_e32 v10, v10
	s_nop 0
	v_mul_f32_e32 v0, v10, v0
	v_mul_f32_e32 v0, v6, v0
	v_cvt_pk_bf16_f32 v0, v0, v1
	global_store_short v[2:3], v0, off offset:64
	v_lshlrev_b32_e32 v0, 16, v109
	v_mul_f32_e32 v6, 0xbfb8aa3b, v0
	v_exp_f32_e32 v6, v6
	s_nop 0
	v_add_f32_e32 v6, 1.0, v6
	v_rcp_f32_e32 v6, v6
	s_nop 0
	v_mul_f32_e32 v0, v6, v0
	v_mul_f32_e32 v0, v7, v0
	v_cvt_pk_bf16_f32 v0, v0, v1
	global_store_short v[2:3], v0, off offset:96
	v_mov_b32_e32 v2, v12
	v_mov_b32_e32 v3, v4
	v_mov_b32_e32 v6, v16
	v_mov_b32_e32 v7, v8
	s_cbranch_vccnz .LBB0_179
	v_mov_b32_e32 v10, v12
	v_mov_b32_e32 v11, v16
	v_mov_b32_e32 v14, v4
	v_mov_b32_e32 v15, v8
	v_pk_add_f32 v[10:11], v[10:11], v[14:15]
	s_nop 0
	v_add_f32_e32 v0, v10, v11
	s_nop 1
	v_mov_b32_dpp v4, v0 quad_perm:[1,0,3,2] row_mask:0xf bank_mask:0xf
	s_waitcnt lgkmcnt(0)
	v_add_f32_e32 v0, v0, v4
	s_nop 1
	v_mov_b32_dpp v4, v0 quad_perm:[2,3,0,1] row_mask:0xf bank_mask:0xf
	s_waitcnt lgkmcnt(0)
	v_add_f32_e32 v0, v0, v4
	s_nop 1
	v_mov_b32_dpp v4, v0 row_half_mirror row_mask:0xf bank_mask:0xf
	s_waitcnt lgkmcnt(0)
	v_add_f32_e32 v0, v0, v4
	s_nop 1
	v_mov_b32_dpp v4, v0 row_mirror row_mask:0xf bank_mask:0xf
	s_waitcnt lgkmcnt(0)
	v_add_f32_e32 v0, v0, v4
	v_mul_f32_e32 v0, 0x3c800000, v0
	v_pk_add_f32 v[2:3], v[2:3], v[0:1] op_sel_hi:[1,0] neg_lo:[0,1] neg_hi:[0,1]
	v_pk_add_f32 v[6:7], v[6:7], v[0:1] op_sel_hi:[1,0] neg_lo:[0,1] neg_hi:[0,1]
; __device__ __forceinline__ float bf2f(unsigned h) { return __uint_as_float(h << 16); }
; __device__ __forceinline__ unsigned pk2(float lo, float hi) { return pg8::cvt_pk_bf16(lo, hi); }
; template <int X> __device__ __forceinline__ float xor_lane(float v) { static_assert(X >= 1 && X <= 16, "xor_lane"); return __int_as_float(__builtin_amdgcn_ds_swizzle(__float_as_int(v), (X << 10) | 0x1F)); }
; __global__ void __launch_bounds__(512, 2) fwd_megakernel(Args args) {
;     ...
;                     for (int r = 0; r < 4; ++r) { const int i = 16 * w4 + 4 * kk + r;
;                         float x0 = O[0][r], x1 = O[1][r], x2 = O[2][r], x3 = O[3][r];
;                         if (grp == 0) { float sm = (x0 + x1) + (x2 + x3); sm += xor_lane<1>(sm); sm += xor_lane<2>(sm); sm += xor_lane<4>(sm); sm += xor_lane<8>(sm);
;                             const float mean = sm * (1.f / 64.f); x0 -= mean; x1 -= mean; x2 -= mean; x3 -= mean; }
;                         float sq = (x0 * x0 + x1 * x1) + (x2 * x2 + x3 * x3); sq += xor_lane<1>(sq); sq += xor_lane<2>(sq); sq += xor_lane<4>(sq); sq += xor_lane<8>(sq);
;                         const float rs = rsqrtf(sq * (1.f / 64.f) + NEPS);
;                         const float xs[4] = {x0 * rs, x1 * rs, x2 * rs, x3 * rs};
;                         u16* yp = XNY + (size_t)(row0 + i) * 1024 + grp * 256 + h * 64 + nn;
; #pragma unroll
;                         for (int et = 0; et < 4; ++et) { const float gate = bf2f(graw[r][et]); const float sg = gate * __builtin_amdgcn_rcpf(1.f + __expf(-gate)); yp[16 * et] = (u16)(pk2(sg * xs[et], 0.f) & 0xffffu); } }
.LBB0_179:
	v_mov_b32_e32 v14, v3
	v_mov_b32_e32 v15, v7
	v_mov_b32_e32 v10, v2
	v_mov_b32_e32 v11, v6
	v_pk_mul_f32 v[14:15], v[14:15], v[14:15]
	s_nop 0
	v_pk_fma_f32 v[10:11], v[10:11], v[10:11], v[14:15]
	s_nop 0
	v_add_f32_e32 v0, v10, v11
	s_nop 1
	v_mov_b32_dpp v4, v0 quad_perm:[1,0,3,2] row_mask:0xf bank_mask:0xf
	s_waitcnt lgkmcnt(0)
	v_add_f32_e32 v0, v0, v4
	s_nop 1
	v_mov_b32_dpp v4, v0 quad_perm:[2,3,0,1] row_mask:0xf bank_mask:0xf
	s_waitcnt lgkmcnt(0)
	v_add_f32_e32 v0, v0, v4
	s_nop 1
	v_mov_b32_dpp v4, v0 row_half_mirror row_mask:0xf bank_mask:0xf
	s_waitcnt lgkmcnt(0)
	v_add_f32_e32 v0, v0, v4
	s_nop 1
	v_mov_b32_dpp v4, v0 row_mirror row_mask:0xf bank_mask:0xf
	s_waitcnt lgkmcnt(0)
	v_add_f32_e32 v0, v0, v4
	v_fmamk_f32 v0, v0, 0x3c800000, v215
	v_cmp_gt_f32_e32 vcc, s77, v0
	v_mul_f32_e32 v4, 0x4b800000, v0
	s_nop 0
	v_cndmask_b32_e32 v0, v0, v4, vcc
	v_rsq_f32_e32 v0, v0
	s_nop 0
	v_mul_f32_e32 v4, 0x45800000, v0
	v_cndmask_b32_e32 v0, v0, v4, vcc
	v_mul_f32_e32 v4, v2, v0
	v_mul_f32_e32 v8, v3, v0
	v_mul_f32_e32 v6, v6, v0
	v_mul_f32_e32 v7, v7, v0
	v_or_b32_e32 v0, 2, v20
	v_lshlrev_b64 v[2:3], 11, v[0:1]
	v_lshlrev_b32_e32 v0, 16, v108
	v_mul_f32_e32 v10, 0xbfb8aa3b, v0
	v_exp_f32_e32 v10, v10
	v_lshl_add_u64 v[2:3], v[18:19], 0, v[2:3]
	s_and_b64 vcc, exec, s[46:47]
	v_add_f32_e32 v10, 1.0, v10
	v_rcp_f32_e32 v10, v10
	s_nop 0
	v_mul_f32_e32 v0, v10, v0
	v_mul_f32_e32 v0, v4, v0
	v_cvt_pk_bf16_f32 v0, v0, v1
	global_store_short v[2:3], v0, off
	v_lshlrev_b32_e32 v0, 16, v107
	v_mul_f32_e32 v4, 0xbfb8aa3b, v0
	v_exp_f32_e32 v4, v4
	s_nop 0
	v_add_f32_e32 v4, 1.0, v4
	v_rcp_f32_e32 v4, v4
	s_nop 0
	v_mul_f32_e32 v0, v4, v0
	v_mul_f32_e32 v0, v8, v0
	v_cvt_pk_bf16_f32 v0, v0, v1
	global_store_short v[2:3], v0, off offset:32
	v_lshlrev_b32_e32 v0, 16, v106
	v_mul_f32_e32 v4, 0xbfb8aa3b, v0
	v_exp_f32_e32 v4, v4
	v_mov_b32_e32 v8, v17
	v_add_f32_e32 v4, 1.0, v4
	v_rcp_f32_e32 v4, v4
	s_nop 0
	v_mul_f32_e32 v0, v4, v0
	v_mul_f32_e32 v0, v6, v0
	v_cvt_pk_bf16_f32 v0, v0, v1
	global_store_short v[2:3], v0, off offset:64
	v_lshlrev_b32_e32 v0, 16, v105
	v_mul_f32_e32 v4, 0xbfb8aa3b, v0
	v_exp_f32_e32 v4, v4
	s_nop 0
	v_add_f32_e32 v4, 1.0, v4
	v_rcp_f32_e32 v4, v4
	s_nop 0
	v_mul_f32_e32 v0, v4, v0
	v_mul_f32_e32 v0, v7, v0
	v_mov_b32_e32 v4, v13
	v_cvt_pk_bf16_f32 v0, v0, v1
	global_store_short v[2:3], v0, off offset:96
	s_cbranch_vccnz .LBB0_146
	v_mov_b32_e32 v16, v13
	v_mov_b32_e32 v2, v5
	v_mov_b32_e32 v3, v9
	v_pk_add_f32 v[2:3], v[16:17], v[2:3]
	s_nop 0
	v_add_f32_e32 v0, v2, v3
	s_nop 1
	v_mov_b32_dpp v2, v0 quad_perm:[1,0,3,2] row_mask:0xf bank_mask:0xf
	s_waitcnt lgkmcnt(0)
	v_add_f32_e32 v0, v0, v2
	s_nop 1
	v_mov_b32_dpp v2, v0 quad_perm:[2,3,0,1] row_mask:0xf bank_mask:0xf
	s_waitcnt lgkmcnt(0)
	v_add_f32_e32 v0, v0, v2
	s_nop 1
	v_mov_b32_dpp v2, v0 row_half_mirror row_mask:0xf bank_mask:0xf
	s_waitcnt lgkmcnt(0)
	v_add_f32_e32 v0, v0, v2
	s_nop 1
	v_mov_b32_dpp v2, v0 row_mirror row_mask:0xf bank_mask:0xf
	s_waitcnt lgkmcnt(0)
	v_add_f32_e32 v0, v0, v2
	v_mul_f32_e32 v0, 0x3c800000, v0
	v_pk_add_f32 v[4:5], v[4:5], v[0:1] op_sel_hi:[1,0] neg_lo:[0,1] neg_hi:[0,1]
	v_pk_add_f32 v[8:9], v[8:9], v[0:1] op_sel_hi:[1,0] neg_lo:[0,1] neg_hi:[0,1]
	s_branch .LBB0_146
